# strategy 7.3: diff-attn and MLA unit epilogues store dwordx4 rows via v_permlane32_swap pairs (half the store instructions)
# speedup vs baseline: 1.0456x; 1.0028x over previous
; template <int KS, int NMAP, int EB, int NKB, int MODE>
; DI void attn_unit(unsigned char* smem, const AttnArgs& a, int t0, int head, int ehalf) {
;     ...
;   if (MODE == AT_DIFF) {
;     float ss = 0.f; const float l1 = a.lam * inv[NMAP - 1];
; #pragma unroll
;     for (int eb = 0; eb < EB; ++eb)
; #pragma unroll
;       for (int i = 0; i < 16; ++i) { const float v = oacc[0][eb][i] * inv[0] - oacc[NMAP - 1][eb][i] * l1; oacc[0][eb][i] = v; ss += v * v; }
;     ss += __shfl_xor(ss, 32);
;     const float rr = rsqrtf(ss * (1.0f / 128.0f) + EPS) * a.oscale;
; #pragma unroll
;     for (int eb = 0; eb < EB; ++eb)
; #pragma unroll
;       for (int g4 = 0; g4 < 4; ++g4) {
;         const int e = eb * 32 + g4 * 8 + 4 * h; const f32x4 g = *(const f32x4*)(a.g0 + e);
;         u32x2 w; w[0] = pk2(oacc[0][eb][4 * g4] * rr * g[0], oacc[0][eb][4 * g4 + 1] * rr * g[1]); w[1] = pk2(oacc[0][eb][4 * g4 + 2] * rr * g[2], oacc[0][eb][4 * g4 + 3] * rr * g[3]);
;         if (!a.nostore) *(u32x2*)(orow + e) = w;
;       }
.LBB0_413:
	global_load_dwordx4 v[22:25], v216, s[4:5]
	global_load_dwordx4 v[26:29], v216, s[4:5] offset:32
	global_load_dwordx4 v[42:45], v216, s[4:5] offset:64
	global_load_dwordx4 v[54:57], v216, s[4:5] offset:96
	global_load_dwordx4 v[58:61], v216, s[4:5] offset:128
	global_load_dwordx4 v[74:77], v216, s[4:5] offset:160
	global_load_dwordx4 v[86:89], v216, s[4:5] offset:192
	global_load_dwordx4 v[90:93], v216, s[4:5] offset:224
	global_load_dwordx4 v[106:109], v216, s[4:5] offset:256
	global_load_dwordx4 v[118:121], v216, s[4:5] offset:288
	global_load_dwordx4 v[122:125], v216, s[4:5] offset:320
	global_load_dwordx4 v[134:137], v216, s[4:5] offset:352
	global_load_dwordx4 v[138:141], v216, s[4:5] offset:384
	global_load_dwordx4 v[142:145], v216, s[4:5] offset:416
	global_load_dwordx4 v[146:149], v216, s[4:5] offset:448
	global_load_dwordx4 v[150:153], v216, s[4:5] offset:480
	s_waitcnt lgkmcnt(0)
	v_add_f32_e32 v8, v8, v9
	v_fmamk_f32 v8, v8, 0x3c000000, v246
	v_cmp_gt_f32_e32 vcc, s67, v8
	v_mul_f32_e32 v9, 0x4b800000, v8
	v_mov_b32_e32 v175, v217
	v_cndmask_b32_e32 v8, v8, v9, vcc
	v_rsq_f32_e32 v8, v8
	s_nop 0
	v_mul_f32_e32 v9, 0x45800000, v8
	v_cndmask_b32_e32 v8, v8, v9, vcc
	v_mul_f32_e32 v10, v189, v8
	v_pk_mul_f32 v[20:21], v[132:133], v[10:11] op_sel_hi:[1,0]
	v_lshl_add_u64 v[8:9], v[172:173], 0, v[174:175]
	v_lshlrev_b32_e32 v162, 1, v174
	v_mov_b32_e32 v163, v217
	v_lshl_add_u64 v[160:161], v[172:173], 0, v[162:163]
	v_pk_mul_f32 v[18:19], v[18:19], v[10:11] op_sel_hi:[1,0]
	v_pk_mul_f32 v[16:17], v[16:17], v[10:11] op_sel_hi:[1,0]
	v_pk_mul_f32 v[6:7], v[6:7], v[10:11] op_sel_hi:[1,0]
	v_pk_mul_f32 v[4:5], v[4:5], v[10:11] op_sel_hi:[1,0]
	v_pk_mul_f32 v[0:1], v[0:1], v[10:11] op_sel_hi:[1,0]
	s_waitcnt vmcnt(15)
	v_mov_b32_e32 v12, v22
	v_mov_b32_e32 v13, v23
	v_mov_b32_e32 v14, v24
	v_mov_b32_e32 v15, v25
	v_pk_mul_f32 v[12:13], v[20:21], v[12:13]
	v_pk_mul_f32 v[20:21], v[128:129], v[10:11] op_sel_hi:[1,0]
	v_cvt_pk_bf16_f32 v156, v12, v13
	v_pk_mul_f32 v[14:15], v[20:21], v[14:15]
	v_pk_mul_f32 v[20:21], v[116:117], v[10:11] op_sel_hi:[1,0]
	v_cvt_pk_bf16_f32 v157, v14, v15
	s_waitcnt vmcnt(14)
	v_mov_b32_e32 v12, v26
	v_mov_b32_e32 v13, v27
	v_mov_b32_e32 v14, v28
	v_mov_b32_e32 v15, v29
	v_pk_mul_f32 v[12:13], v[20:21], v[12:13]
	v_pk_mul_f32 v[20:21], v[114:115], v[10:11] op_sel_hi:[1,0]
	v_cvt_pk_bf16_f32 v158, v12, v13
	v_pk_mul_f32 v[14:15], v[20:21], v[14:15]
	v_pk_mul_f32 v[20:21], v[112:113], v[10:11] op_sel_hi:[1,0]
	v_cvt_pk_bf16_f32 v159, v14, v15
	s_nop 1
	v_permlane32_swap_b32_e32 v156, v158
	v_permlane32_swap_b32_e32 v157, v159
	global_store_dwordx4 v[160:161], v[156:159], off
	s_waitcnt vmcnt(14)
	v_mov_b32_e32 v12, v42
	v_mov_b32_e32 v13, v43
	v_mov_b32_e32 v14, v44
	v_mov_b32_e32 v15, v45
	v_pk_mul_f32 v[12:13], v[20:21], v[12:13]
	v_pk_mul_f32 v[20:21], v[104:105], v[10:11] op_sel_hi:[1,0]
	v_cvt_pk_bf16_f32 v156, v12, v13
	v_pk_mul_f32 v[14:15], v[20:21], v[14:15]
	v_pk_mul_f32 v[20:21], v[102:103], v[10:11] op_sel_hi:[1,0]
	v_cvt_pk_bf16_f32 v157, v14, v15
	s_waitcnt vmcnt(13)
	v_mov_b32_e32 v12, v54
	v_mov_b32_e32 v13, v55
	v_mov_b32_e32 v14, v56
	v_mov_b32_e32 v15, v57
	v_pk_mul_f32 v[12:13], v[20:21], v[12:13]
	v_pk_mul_f32 v[20:21], v[100:101], v[10:11] op_sel_hi:[1,0]
	v_cvt_pk_bf16_f32 v158, v12, v13
	v_pk_mul_f32 v[14:15], v[20:21], v[14:15]
	v_pk_mul_f32 v[20:21], v[98:99], v[10:11] op_sel_hi:[1,0]
	v_cvt_pk_bf16_f32 v159, v14, v15
	s_nop 1
	v_permlane32_swap_b32_e32 v156, v158
	v_permlane32_swap_b32_e32 v157, v159
	global_store_dwordx4 v[160:161], v[156:159], off offset:32
	s_waitcnt vmcnt(13)
	v_mov_b32_e32 v12, v58
	v_mov_b32_e32 v13, v59
	v_mov_b32_e32 v14, v60
	v_mov_b32_e32 v15, v61
	v_pk_mul_f32 v[12:13], v[20:21], v[12:13]
	v_pk_mul_f32 v[20:21], v[96:97], v[10:11] op_sel_hi:[1,0]
	v_cvt_pk_bf16_f32 v156, v12, v13
	v_pk_mul_f32 v[14:15], v[20:21], v[14:15]
	v_pk_mul_f32 v[20:21], v[84:85], v[10:11] op_sel_hi:[1,0]
	v_cvt_pk_bf16_f32 v157, v14, v15
	s_waitcnt vmcnt(12)
	v_mov_b32_e32 v12, v74
	v_mov_b32_e32 v13, v75
	v_mov_b32_e32 v14, v76
	v_mov_b32_e32 v15, v77
	v_pk_mul_f32 v[12:13], v[20:21], v[12:13]
	v_pk_mul_f32 v[20:21], v[82:83], v[10:11] op_sel_hi:[1,0]
	v_cvt_pk_bf16_f32 v158, v12, v13
	v_pk_mul_f32 v[14:15], v[20:21], v[14:15]
	v_pk_mul_f32 v[20:21], v[80:81], v[10:11] op_sel_hi:[1,0]
	v_cvt_pk_bf16_f32 v159, v14, v15
	s_nop 1
	v_permlane32_swap_b32_e32 v156, v158
	v_permlane32_swap_b32_e32 v157, v159
	global_store_dwordx4 v[160:161], v[156:159], off offset:64
	s_waitcnt vmcnt(12)
; template <int KS, int NMAP, int EB, int NKB, int MODE>
; DI void attn_unit(unsigned char* smem, const AttnArgs& a, int t0, int head, int ehalf) {
;     ...
; #pragma unroll
;     for (int eb = 0; eb < EB; ++eb)
; #pragma unroll
;       for (int g4 = 0; g4 < 4; ++g4) {
;         const int e = eb * 32 + g4 * 8 + 4 * h; const f32x4 g = *(const f32x4*)(a.g0 + e);
;         u32x2 w; w[0] = pk2(oacc[0][eb][4 * g4] * rr * g[0], oacc[0][eb][4 * g4 + 1] * rr * g[1]); w[1] = pk2(oacc[0][eb][4 * g4 + 2] * rr * g[2], oacc[0][eb][4 * g4 + 3] * rr * g[3]);
;         if (!a.nostore) *(u32x2*)(orow + e) = w;
;       }
	v_mov_b32_e32 v12, v86
	v_mov_b32_e32 v13, v87
	v_mov_b32_e32 v14, v88
	v_mov_b32_e32 v15, v89
	v_pk_mul_f32 v[12:13], v[20:21], v[12:13]
	v_pk_mul_f32 v[20:21], v[72:73], v[10:11] op_sel_hi:[1,0]
	v_cvt_pk_bf16_f32 v156, v12, v13
	v_pk_mul_f32 v[14:15], v[20:21], v[14:15]
	v_pk_mul_f32 v[20:21], v[70:71], v[10:11] op_sel_hi:[1,0]
	v_cvt_pk_bf16_f32 v157, v14, v15
	s_waitcnt vmcnt(11)
	v_mov_b32_e32 v12, v90
	v_mov_b32_e32 v13, v91
	v_mov_b32_e32 v14, v92
	v_mov_b32_e32 v15, v93
	v_pk_mul_f32 v[12:13], v[20:21], v[12:13]
	v_pk_mul_f32 v[20:21], v[68:69], v[10:11] op_sel_hi:[1,0]
	v_cvt_pk_bf16_f32 v158, v12, v13
	v_pk_mul_f32 v[14:15], v[20:21], v[14:15]
	v_pk_mul_f32 v[20:21], v[66:67], v[10:11] op_sel_hi:[1,0]
	v_cvt_pk_bf16_f32 v159, v14, v15
	s_nop 1
	v_permlane32_swap_b32_e32 v156, v158
	v_permlane32_swap_b32_e32 v157, v159
	global_store_dwordx4 v[160:161], v[156:159], off offset:96
	s_waitcnt vmcnt(11)
	v_mov_b32_e32 v12, v106
	v_mov_b32_e32 v13, v107
	v_mov_b32_e32 v14, v108
	v_mov_b32_e32 v15, v109
	v_pk_mul_f32 v[12:13], v[20:21], v[12:13]
	v_pk_mul_f32 v[20:21], v[64:65], v[10:11] op_sel_hi:[1,0]
	v_cvt_pk_bf16_f32 v156, v12, v13
	v_pk_mul_f32 v[14:15], v[20:21], v[14:15]
	v_pk_mul_f32 v[20:21], v[52:53], v[10:11] op_sel_hi:[1,0]
	v_cvt_pk_bf16_f32 v157, v14, v15
	s_waitcnt vmcnt(10)
	v_mov_b32_e32 v12, v118
	v_mov_b32_e32 v13, v119
	v_mov_b32_e32 v14, v120
	v_mov_b32_e32 v15, v121
	v_pk_mul_f32 v[12:13], v[20:21], v[12:13]
	v_pk_mul_f32 v[20:21], v[50:51], v[10:11] op_sel_hi:[1,0]
	v_cvt_pk_bf16_f32 v158, v12, v13
	v_pk_mul_f32 v[14:15], v[20:21], v[14:15]
	v_pk_mul_f32 v[20:21], v[48:49], v[10:11] op_sel_hi:[1,0]
	v_cvt_pk_bf16_f32 v159, v14, v15
	s_nop 1
	v_permlane32_swap_b32_e32 v156, v158
	v_permlane32_swap_b32_e32 v157, v159
	global_store_dwordx4 v[160:161], v[156:159], off offset:128
	s_waitcnt vmcnt(10)
	v_mov_b32_e32 v12, v122
	v_mov_b32_e32 v13, v123
	v_mov_b32_e32 v14, v124
	v_mov_b32_e32 v15, v125
	v_pk_mul_f32 v[12:13], v[20:21], v[12:13]
	v_pk_mul_f32 v[20:21], v[40:41], v[10:11] op_sel_hi:[1,0]
	v_cvt_pk_bf16_f32 v156, v12, v13
	v_pk_mul_f32 v[14:15], v[20:21], v[14:15]
	v_pk_mul_f32 v[20:21], v[38:39], v[10:11] op_sel_hi:[1,0]
	v_cvt_pk_bf16_f32 v157, v14, v15
	s_waitcnt vmcnt(9)
	v_mov_b32_e32 v12, v134
	v_mov_b32_e32 v13, v135
	v_mov_b32_e32 v14, v136
	v_mov_b32_e32 v15, v137
	v_pk_mul_f32 v[12:13], v[20:21], v[12:13]
	v_pk_mul_f32 v[20:21], v[36:37], v[10:11] op_sel_hi:[1,0]
	v_cvt_pk_bf16_f32 v158, v12, v13
	v_pk_mul_f32 v[14:15], v[20:21], v[14:15]
	v_pk_mul_f32 v[20:21], v[34:35], v[10:11] op_sel_hi:[1,0]
	v_cvt_pk_bf16_f32 v159, v14, v15
	s_nop 1
	v_permlane32_swap_b32_e32 v156, v158
	v_permlane32_swap_b32_e32 v157, v159
	global_store_dwordx4 v[160:161], v[156:159], off offset:160
	s_waitcnt vmcnt(9)
	v_mov_b32_e32 v12, v138
	v_mov_b32_e32 v13, v139
	v_mov_b32_e32 v14, v140
	v_mov_b32_e32 v15, v141
	v_pk_mul_f32 v[12:13], v[20:21], v[12:13]
	v_pk_mul_f32 v[20:21], v[32:33], v[10:11] op_sel_hi:[1,0]
	v_cvt_pk_bf16_f32 v156, v12, v13
	v_pk_mul_f32 v[14:15], v[20:21], v[14:15]
	s_nop 0
	v_cvt_pk_bf16_f32 v157, v14, v15
	s_waitcnt vmcnt(8)
	v_mov_b32_e32 v12, v142
	v_mov_b32_e32 v13, v143
	v_mov_b32_e32 v14, v144
	v_mov_b32_e32 v15, v145
	v_pk_mul_f32 v[12:13], v[18:19], v[12:13]
	v_pk_mul_f32 v[14:15], v[16:17], v[14:15]
	v_cvt_pk_bf16_f32 v158, v12, v13
	v_cvt_pk_bf16_f32 v159, v14, v15
	s_nop 1
	v_permlane32_swap_b32_e32 v156, v158
	v_permlane32_swap_b32_e32 v157, v159
	global_store_dwordx4 v[160:161], v[156:159], off offset:192
	s_waitcnt vmcnt(8)
	v_mov_b32_e32 v12, v146
	v_mov_b32_e32 v13, v147
	v_mov_b32_e32 v14, v148
	v_mov_b32_e32 v15, v149
	v_pk_mul_f32 v[6:7], v[6:7], v[12:13]
	v_pk_mul_f32 v[4:5], v[4:5], v[14:15]
	v_cvt_pk_bf16_f32 v156, v6, v7
	v_cvt_pk_bf16_f32 v157, v4, v5
	v_pk_mul_f32 v[6:7], v[2:3], v[10:11] op_sel_hi:[1,0]
	s_waitcnt vmcnt(7)
	v_mov_b32_e32 v2, v150
	v_mov_b32_e32 v3, v151
	v_mov_b32_e32 v4, v152
	v_mov_b32_e32 v5, v153
	v_pk_mul_f32 v[2:3], v[6:7], v[2:3]
	v_pk_mul_f32 v[0:1], v[0:1], v[4:5]
	v_cvt_pk_bf16_f32 v158, v2, v3
	v_cvt_pk_bf16_f32 v159, v0, v1
	s_nop 1
	v_permlane32_swap_b32_e32 v156, v158
	v_permlane32_swap_b32_e32 v157, v159
	global_store_dwordx4 v[160:161], v[156:159], off offset:224
	s_branch .LBB0_397

; #define MFMA(a, b, c) __builtin_amdgcn_mfma_f32_32x32x16_bf16((a), (b), (c), 0, 0, 0)
; template <int KS, int NMAP, int EB, int NKB, int MODE>
; DI void attn_unit(unsigned char* smem, const AttnArgs& a, int t0, int head, int ehalf) {
;     ...
;     for (int kb = 0; kb < NKB; ++kb) {
;       bf16x8 pf[NMAP][2];
;       f32x16 cinit;
;       if (MODE == AT_DIFF) {
;         const float dbase = (float)(posq - kt * KT - 32 * kb - 8 * h);
; #pragma unroll
;         for (int i = 0; i < 16; ++i) { const float d = dbase - (float)(16 * (i >> 3) + (i & 7)); cinit[i] = fmaf(-slope2, fabsf(d), negM); }
;       } else {
; #pragma unroll
;         for (int i = 0; i < 16; ++i) cinit[i] = negM;
;       }
; #pragma unroll
;       for (int c = 0; c < NMAP; ++c) {
;         f32x16 sacc;
; #pragma unroll
;         for (int s = 0; s < KS; ++s) {
;           const bf16x8 kf = *(const bf16x8*)(ks + (32 * kb + r) * KP + (c * KS + s) * 32 + 16 * h);
;           const bf16x8 qv = QLDS ? *(const bf16x8*)(qs + qoff + (c * KS + s) * 32) : qf[QLDS ? 0 : c * KS + s];
;           sacc = (s == 0) ? MFMA(kf, qv, cinit) : MFMA(kf, qv, sacc);
;         }
;         float ls = 0.f;
; #pragma unroll
;         for (int i = 0; i < 16; ++i) { sacc[i] = __builtin_amdgcn_exp2f(sacc[i]); ls += sacc[i]; }
;         lsum[c] += ls;
; #pragma unroll
;         for (int cc = 0; cc < 2; ++cc) { u32x4 u;
; #pragma unroll
;           for (int j = 0; j < 4; ++j) u[j] = pk2(sacc[8 * cc + 2 * j], sacc[8 * cc + 2 * j + 1]);
;           pf[c][cc] = __builtin_bit_cast(bf16x8, u); }
;       }
; #pragma unroll
;       for (int eb = 0; eb < EB; ++eb)
; #pragma unroll
;         for (int cc = 0; cc < 2; ++cc) {
;           const bf16x8 vf = *(const bf16x8*)(vs + (eb * 32 + r) * VP + (32 * kb + 16 * cc + 8 * h) * 2);
; #pragma unroll
;           for (int c = 0; c < NMAP; ++c) oacc[c][eb] = MFMA(vf, pf[c][cc], oacc[c][eb]);
;         }
;     }
.LBB0_486:
	s_mulk_i32 s1, 0x5800
	v_add_u32_e32 v133, s1, v132
	v_add_u32_e32 v143, v133, v126
	v_add_u32_e32 v133, v133, v127
	ds_read_b128 v[174:177], v143
	ds_read_b128 v[178:181], v143 offset:32
	ds_read_b128 v[182:185], v143 offset:64
	ds_read_b128 v[186:189], v143 offset:96
	ds_read_b128 v[190:193], v143 offset:128
	ds_read_b128 v[194:197], v143 offset:160
	ds_read_b128 v[198:201], v143 offset:6656
	ds_read_b128 v[202:205], v143 offset:6688
	ds_read_b128 v[206:209], v143 offset:6720
	ds_read_b128 v[210:213], v143 offset:6752
	ds_read_b128 v[220:223], v143 offset:6784
	ds_read_b128 v[224:227], v143 offset:6816
	s_add_i32 s50, s50, 64
	s_cmp_lg_u32 s11, s12
	s_waitcnt lgkmcnt(11)
	v_mfma_f32_32x32x16_bf16 v[64:79], v[174:177], v[88:91], v[0:15]
	s_waitcnt lgkmcnt(10)
	v_mfma_f32_32x32x16_bf16 v[64:79], v[178:181], v[92:95], v[64:79]
	s_waitcnt lgkmcnt(9)
	v_mfma_f32_32x32x16_bf16 v[64:79], v[182:185], v[96:99], v[64:79]
	s_waitcnt lgkmcnt(8)
	v_mfma_f32_32x32x16_bf16 v[64:79], v[186:189], v[100:103], v[64:79]
	s_waitcnt lgkmcnt(7)
	v_mfma_f32_32x32x16_bf16 v[64:79], v[190:193], v[104:107], v[64:79]
	s_waitcnt lgkmcnt(6)
	v_mfma_f32_32x32x16_bf16 v[64:79], v[194:197], v[108:111], v[64:79]
	s_waitcnt lgkmcnt(5)
	v_mfma_f32_32x32x16_bf16 v[48:63], v[198:201], v[88:91], v[0:15]
	ds_read_b128 v[228:231], v133 offset:13312
	ds_read_b128 v[232:235], v133 offset:17920
	ds_read_b128 v[236:239], v133 offset:13344
	ds_read_b128 v[240:243], v133 offset:17952
	s_waitcnt lgkmcnt(8)
	v_mfma_f32_32x32x16_bf16 v[48:63], v[202:205], v[92:95], v[48:63]
	ds_read_b128 v[174:177], v133 offset:13376
	ds_read_b128 v[178:181], v133 offset:17984
	ds_read_b128 v[182:185], v133 offset:13408
	ds_read_b128 v[186:189], v133 offset:18016
	s_waitcnt lgkmcnt(11)
	v_mfma_f32_32x32x16_bf16 v[48:63], v[206:209], v[96:99], v[48:63]
	v_exp_f32_e32 v151, v64
	v_exp_f32_e32 v152, v65
	v_exp_f32_e32 v153, v66
	v_exp_f32_e32 v154, v67
	s_waitcnt lgkmcnt(10)
	v_mfma_f32_32x32x16_bf16 v[48:63], v[210:213], v[100:103], v[48:63]
	v_exp_f32_e32 v155, v68
	v_exp_f32_e32 v156, v69
	v_exp_f32_e32 v157, v70
	v_exp_f32_e32 v158, v71
	s_waitcnt lgkmcnt(9)
	v_mfma_f32_32x32x16_bf16 v[48:63], v[220:223], v[104:107], v[48:63]
	v_cvt_pk_bf16_f32 v134, v151, v152
	v_cvt_pk_bf16_f32 v135, v153, v154
	v_cvt_pk_bf16_f32 v136, v155, v156
	v_cvt_pk_bf16_f32 v137, v157, v158
	v_exp_f32_e32 v159, v72
	v_exp_f32_e32 v160, v73
	s_waitcnt lgkmcnt(8)
	v_mfma_f32_32x32x16_bf16 v[48:63], v[224:227], v[108:111], v[48:63]
	v_exp_f32_e32 v161, v74
	v_exp_f32_e32 v162, v75
	v_exp_f32_e32 v163, v76
	v_exp_f32_e32 v164, v77
	s_waitcnt lgkmcnt(7)
	v_mfma_f32_32x32x16_bf16 v[32:47], v[228:231], v[134:137], v[32:47]
	v_exp_f32_e32 v165, v78
	v_exp_f32_e32 v166, v79
	v_cvt_pk_bf16_f32 v138, v159, v160
	v_cvt_pk_bf16_f32 v139, v161, v162
	v_cvt_pk_bf16_f32 v140, v163, v164
	v_add_f32_e32 v133, v151, v152
	v_cvt_pk_bf16_f32 v141, v165, v166
	v_add_f32_e32 v124, v124, v153
	s_waitcnt lgkmcnt(6)
	v_mfma_f32_32x32x16_bf16 v[16:31], v[232:235], v[134:137], v[16:31]
	v_exp_f32_e32 v167, v48
	v_exp_f32_e32 v168, v49
	v_exp_f32_e32 v169, v50
	v_exp_f32_e32 v170, v51
	s_waitcnt lgkmcnt(5)
	v_mfma_f32_32x32x16_bf16 v[32:47], v[236:239], v[138:141], v[32:47]
	v_exp_f32_e32 v171, v52
	v_exp_f32_e32 v172, v53
	v_exp_f32_e32 v142, v54
	v_exp_f32_e32 v143, v55
	s_waitcnt lgkmcnt(4)
	v_mfma_f32_32x32x16_bf16 v[16:31], v[240:243], v[138:141], v[16:31]
	v_cvt_pk_bf16_f32 v64, v167, v168
	v_cvt_pk_bf16_f32 v65, v169, v170
	v_cvt_pk_bf16_f32 v66, v171, v172
	v_cvt_pk_bf16_f32 v67, v142, v143
	v_exp_f32_e32 v144, v56
	v_exp_f32_e32 v145, v57
	s_waitcnt lgkmcnt(3)
	v_mfma_f32_32x32x16_bf16 v[32:47], v[174:177], v[64:67], v[32:47]
	v_exp_f32_e32 v244, v58
	v_exp_f32_e32 v245, v59
	v_exp_f32_e32 v248, v60
	v_exp_f32_e32 v249, v61
	s_waitcnt lgkmcnt(2)
	v_mfma_f32_32x32x16_bf16 v[16:31], v[178:181], v[64:67], v[16:31]
	v_exp_f32_e32 v251, v62
	v_exp_f32_e32 v252, v63
	v_cvt_pk_bf16_f32 v68, v144, v145
	v_cvt_pk_bf16_f32 v69, v244, v245
	v_cvt_pk_bf16_f32 v70, v248, v249
	v_add_f32_e32 v133, v133, v154
	v_cvt_pk_bf16_f32 v71, v251, v252
	v_add_f32_e32 v124, v124, v155
	v_add_f32_e32 v133, v133, v156
	s_waitcnt lgkmcnt(1)
	v_mfma_f32_32x32x16_bf16 v[32:47], v[182:185], v[68:71], v[32:47]
	v_add_f32_e32 v124, v124, v157
	v_add_f32_e32 v133, v133, v158
	v_add_f32_e32 v124, v124, v159
	v_add_f32_e32 v133, v133, v160
	v_add_f32_e32 v124, v124, v161
	v_add_f32_e32 v133, v133, v162
	v_add_f32_e32 v124, v124, v163
	v_add_f32_e32 v133, v133, v164
	s_waitcnt lgkmcnt(0)
	s_barrier
; template <int KS, int NMAP, int EB, int NKB, int MODE>
; DI void attn_unit(unsigned char* smem, const AttnArgs& a, int t0, int head, int ehalf) {
;     ...
;     if (DBUF) __syncthreads();
;   }
;     ...
;   float inv[NMAP];
; #pragma unroll
;   for (int c = 0; c < NMAP; ++c) { float l = lsum[c]; l += __shfl_xor(l, 32); inv[c] = 1.0f / l; }
;     ...
;   } else {
; #pragma unroll
;     for (int eb = 0; eb < EB; ++eb)
; #pragma unroll
;       for (int g4 = 0; g4 < 4; ++g4) {
;         const int e = eb * 32 + g4 * 8 + 4 * h; const float iv = inv[0];
;         u32x2 w; w[0] = pk2(oacc[0][eb][4 * g4] * iv, oacc[0][eb][4 * g4 + 1] * iv); w[1] = pk2(oacc[0][eb][4 * g4 + 2] * iv, oacc[0][eb][4 * g4 + 3] * iv);
;         *(u32x2*)(orow + e) = w;
;       }
;   }
	v_mfma_f32_32x32x16_bf16 v[16:31], v[186:189], v[68:71], v[16:31]
	v_add_f32_e32 v124, v124, v165
	v_add_f32_e32 v133, v133, v166
	v_add_f32_e32 v124, v124, v167
	v_add_f32_e32 v133, v133, v168
	v_add_f32_e32 v124, v124, v169
	v_add_f32_e32 v133, v133, v170
	v_add_f32_e32 v124, v124, v171
	v_add_f32_e32 v133, v133, v172
	v_add_f32_e32 v124, v124, v142
	v_add_f32_e32 v133, v133, v143
	v_add_f32_e32 v124, v124, v144
	v_add_f32_e32 v133, v133, v145
	v_add_f32_e32 v124, v124, v244
	v_add_f32_e32 v133, v133, v245
	v_add_f32_e32 v124, v124, v248
	v_add_f32_e32 v133, v133, v249
	v_add_f32_e32 v124, v124, v251
	v_add_f32_e32 v133, v133, v252
	v_add_f32_e32 v124, v124, v133
	s_cbranch_scc1 .LBB0_474
	ds_bpermute_b32 v50, v147, v124
	v_lshlrev_b64 v[48:49], 10, v[116:117]
	v_lshl_add_u64 v[48:49], s[54:55], 0, v[48:49]
	s_lshl_b32 s50, s10, 1
	v_lshl_add_u64 v[48:49], v[48:49], 0, s[50:51]
	s_waitcnt lgkmcnt(0)
	v_add_f32_e32 v50, v124, v50
	v_div_scale_f32 v51, s[0:1], v50, v50, 1.0
	v_rcp_f32_e32 v52, v51
	v_lshlrev_b32_e32 v216, 3, v146
	s_mov_b64 s[2:3], 0
	v_fma_f32 v53, -v51, v52, 1.0
	v_fmac_f32_e32 v52, v53, v52
	v_div_scale_f32 v53, vcc, 1.0, v50, 1.0
	v_mul_f32_e32 v54, v53, v52
	v_fma_f32 v55, -v51, v54, v53
	v_fmac_f32_e32 v54, v55, v52
	v_fma_f32 v51, -v51, v54, v53
	v_div_fmas_f32 v51, v51, v52, v54
	v_div_fixup_f32 v50, v51, v50, 1.0
	v_mul_f32_e32 v32, v32, v50
	v_mul_f32_e32 v33, v33, v50
	v_mul_f32_e32 v16, v16, v50
	v_mul_f32_e32 v17, v17, v50
	v_cvt_pk_bf16_f32 v176, v32, v33
	v_mul_f32_e32 v33, v34, v50
	v_mul_f32_e32 v34, v35, v50
	v_cvt_pk_bf16_f32 v180, v16, v17
	v_mul_f32_e32 v17, v18, v50
	v_mul_f32_e32 v18, v19, v50
	v_cvt_pk_bf16_f32 v177, v33, v34
	v_lshl_add_u64 v[34:35], v[48:49], 0, v[216:217]
	v_lshlrev_b32_e32 v186, 4, v146
	v_mov_b32_e32 v187, v217
	v_lshl_add_u64 v[184:185], v[48:49], 0, v[186:187]
	v_cvt_pk_bf16_f32 v181, v17, v18
	v_mul_f32_e32 v32, v36, v50
	v_mul_f32_e32 v33, v37, v50
	v_mul_f32_e32 v16, v20, v50
	v_mul_f32_e32 v17, v21, v50
	v_cvt_pk_bf16_f32 v178, v32, v33
	v_mul_f32_e32 v33, v38, v50
	v_mul_f32_e32 v36, v39, v50
	v_cvt_pk_bf16_f32 v182, v16, v17
	v_mul_f32_e32 v17, v22, v50
	v_mul_f32_e32 v18, v23, v50
	v_cvt_pk_bf16_f32 v179, v33, v36
	v_cvt_pk_bf16_f32 v183, v17, v18
	s_nop 1
	v_permlane32_swap_b32_e32 v176, v178
	v_permlane32_swap_b32_e32 v177, v179
	global_store_dwordx4 v[184:185], v[176:179], off
	v_mul_f32_e32 v32, v40, v50
	v_mul_f32_e32 v33, v41, v50
	s_nop 1
	v_permlane32_swap_b32_e32 v180, v182
	v_permlane32_swap_b32_e32 v181, v183
	global_store_dwordx4 v[184:185], v[180:183], off offset:64
	v_mul_f32_e32 v16, v24, v50
	v_mul_f32_e32 v17, v25, v50
	v_cvt_pk_bf16_f32 v176, v32, v33
	v_mul_f32_e32 v33, v42, v50
	v_mul_f32_e32 v36, v43, v50
	v_cvt_pk_bf16_f32 v180, v16, v17
	v_mul_f32_e32 v17, v26, v50
	v_mul_f32_e32 v18, v27, v50
	v_cvt_pk_bf16_f32 v177, v33, v36
	v_cvt_pk_bf16_f32 v181, v17, v18
	v_mul_f32_e32 v32, v44, v50
	v_mul_f32_e32 v33, v45, v50
	v_mul_f32_e32 v16, v28, v50
	v_mul_f32_e32 v17, v29, v50
	v_cvt_pk_bf16_f32 v178, v32, v33
	v_mul_f32_e32 v33, v46, v50
	v_mul_f32_e32 v36, v47, v50
	v_cvt_pk_bf16_f32 v182, v16, v17
	v_mul_f32_e32 v17, v30, v50
	v_mul_f32_e32 v18, v31, v50
	v_cvt_pk_bf16_f32 v179, v33, v36
	v_cvt_pk_bf16_f32 v183, v17, v18
	s_nop 1
	v_permlane32_swap_b32_e32 v176, v178
	v_permlane32_swap_b32_e32 v177, v179
	global_store_dwordx4 v[184:185], v[176:179], off offset:32
	s_nop 1
	v_permlane32_swap_b32_e32 v180, v182
	v_permlane32_swap_b32_e32 v181, v183
	global_store_dwordx4 v[184:185], v[180:183], off offset:96
	s_branch .LBB0_453
